# multi-unit GEMM loops: per-unit accumulator zeroing with 64 v_mov_b64 instead of 128 v_mov_b32
# speedup vs baseline: 1.0128x; 1.0020x over previous
.LBB0_200:
	s_ashr_i32 s17, s16, 31
	s_lshl_b64 s[18:19], s[16:17], 19
	s_add_u32 s18, s58, s18
	s_addc_u32 s19, s59, s19
	s_and_b64 s[20:21], s[0:1], exec
	s_cselect_b32 s17, s19, s25
	s_cselect_b32 s45, s18, s24
	s_ashr_i32 s13, s12, 31
	s_lshl_b64 s[20:21], s[12:13], 19
	s_add_u32 s20, s92, s20
	s_addc_u32 s21, s93, s21
	s_and_b64 s[30:31], s[0:1], exec
	s_cselect_b32 s13, s21, s29
	s_cselect_b32 s46, s20, s28
	s_add_u32 s24, s24, 0x40080
	s_addc_u32 s25, s25, 0
	s_add_u32 s47, s28, 0x100
	v_mov_b64_e32 v[2:3], 0
	s_addc_u32 s48, s29, 0
	s_mov_b32 s49, -2
	v_mov_b64_e32 v[4:5], v[2:3]
	v_mov_b64_e32 v[6:7], v[2:3]
	v_mov_b64_e32 v[8:9], v[2:3]
	v_mov_b64_e32 v[10:11], v[2:3]
	v_mov_b64_e32 v[12:13], v[2:3]
	v_mov_b64_e32 v[14:15], v[2:3]
	v_mov_b64_e32 v[16:17], v[2:3]
	v_mov_b64_e32 v[18:19], v[2:3]
	v_mov_b64_e32 v[20:21], v[2:3]
	v_mov_b64_e32 v[22:23], v[2:3]
	v_mov_b64_e32 v[24:25], v[2:3]
	v_mov_b64_e32 v[26:27], v[2:3]
	v_mov_b64_e32 v[28:29], v[2:3]
	v_mov_b64_e32 v[30:31], v[2:3]
	v_mov_b64_e32 v[32:33], v[2:3]
	v_mov_b64_e32 v[34:35], v[2:3]
	v_mov_b64_e32 v[36:37], v[2:3]
	v_mov_b64_e32 v[38:39], v[2:3]
	v_mov_b64_e32 v[40:41], v[2:3]
	v_mov_b64_e32 v[42:43], v[2:3]
	v_mov_b64_e32 v[44:45], v[2:3]
	v_mov_b64_e32 v[46:47], v[2:3]
	v_mov_b64_e32 v[48:49], v[2:3]
	v_mov_b64_e32 v[50:51], v[2:3]
	v_mov_b64_e32 v[52:53], v[2:3]
	v_mov_b64_e32 v[54:55], v[2:3]
	v_mov_b64_e32 v[56:57], v[2:3]
	v_mov_b64_e32 v[58:59], v[2:3]
	v_mov_b64_e32 v[60:61], v[2:3]
	v_mov_b64_e32 v[62:63], v[2:3]
	v_mov_b64_e32 v[64:65], v[2:3]
	v_mov_b64_e32 v[66:67], v[2:3]
	v_mov_b64_e32 v[68:69], v[2:3]
	v_mov_b64_e32 v[70:71], v[2:3]
	v_mov_b64_e32 v[72:73], v[2:3]
	v_mov_b64_e32 v[74:75], v[2:3]
	v_mov_b64_e32 v[76:77], v[2:3]
	v_mov_b64_e32 v[78:79], v[2:3]
	v_mov_b64_e32 v[80:81], v[2:3]
	v_mov_b64_e32 v[82:83], v[2:3]
	v_mov_b64_e32 v[84:85], v[2:3]
	v_mov_b64_e32 v[86:87], v[2:3]
	v_mov_b64_e32 v[88:89], v[2:3]
	v_mov_b64_e32 v[90:91], v[2:3]
	v_mov_b64_e32 v[92:93], v[2:3]
	v_mov_b64_e32 v[94:95], v[2:3]
	v_mov_b64_e32 v[96:97], v[2:3]
	v_mov_b64_e32 v[98:99], v[2:3]
	v_mov_b64_e32 v[100:101], v[2:3]
	v_mov_b64_e32 v[102:103], v[2:3]
	v_mov_b64_e32 v[104:105], v[2:3]
	v_mov_b64_e32 v[106:107], v[2:3]
	v_mov_b64_e32 v[108:109], v[2:3]
	v_mov_b64_e32 v[110:111], v[2:3]
	v_mov_b64_e32 v[112:113], v[2:3]
	v_mov_b64_e32 v[114:115], v[2:3]
	v_mov_b64_e32 v[116:117], v[2:3]
	v_mov_b64_e32 v[118:119], v[2:3]
	v_mov_b64_e32 v[120:121], v[2:3]
	v_mov_b64_e32 v[122:123], v[2:3]
	v_mov_b64_e32 v[124:125], v[2:3]
	v_mov_b64_e32 v[126:127], v[2:3]
	v_mov_b64_e32 v[128:129], v[2:3]

.LBB0_711:
	s_ashr_i32 s19, s18, 31
	s_lshl_b64 s[20:21], s[18:19], 19
	s_add_u32 s20, s58, s20
	s_addc_u32 s21, s59, s21
	s_and_b64 s[22:23], s[0:1], exec
	s_cselect_b32 s19, s21, s29
	s_cselect_b32 s47, s20, s28
	s_ashr_i32 s17, s16, 31
	s_lshl_b64 s[22:23], s[16:17], 19
	v_readlane_b32 s48, v251, 4
	v_readlane_b32 s49, v251, 5
	s_add_u32 s22, s48, s22
	s_addc_u32 s23, s49, s23
	s_and_b64 s[48:49], s[0:1], exec
	s_cselect_b32 s17, s23, s31
	s_cselect_b32 s48, s22, s30
	s_add_u32 s28, s28, 0x40080
	s_addc_u32 s29, s29, 0
	s_add_u32 s49, s30, 0x100
	v_mov_b64_e32 v[2:3], 0
	s_addc_u32 s50, s31, 0
	s_mov_b32 s51, -2
	v_mov_b64_e32 v[4:5], v[2:3]
	v_mov_b64_e32 v[6:7], v[2:3]
	v_mov_b64_e32 v[8:9], v[2:3]
	v_mov_b64_e32 v[10:11], v[2:3]
	v_mov_b64_e32 v[12:13], v[2:3]
	v_mov_b64_e32 v[14:15], v[2:3]
	v_mov_b64_e32 v[16:17], v[2:3]
	v_mov_b64_e32 v[18:19], v[2:3]
	v_mov_b64_e32 v[20:21], v[2:3]
	v_mov_b64_e32 v[22:23], v[2:3]
	v_mov_b64_e32 v[24:25], v[2:3]
	v_mov_b64_e32 v[26:27], v[2:3]
	v_mov_b64_e32 v[28:29], v[2:3]
	v_mov_b64_e32 v[30:31], v[2:3]
	v_mov_b64_e32 v[32:33], v[2:3]
	v_mov_b64_e32 v[34:35], v[2:3]
	v_mov_b64_e32 v[36:37], v[2:3]
	v_mov_b64_e32 v[38:39], v[2:3]
	v_mov_b64_e32 v[40:41], v[2:3]
	v_mov_b64_e32 v[42:43], v[2:3]
	v_mov_b64_e32 v[44:45], v[2:3]
	v_mov_b64_e32 v[46:47], v[2:3]
	v_mov_b64_e32 v[48:49], v[2:3]
	v_mov_b64_e32 v[50:51], v[2:3]
	v_mov_b64_e32 v[52:53], v[2:3]
	v_mov_b64_e32 v[54:55], v[2:3]
	v_mov_b64_e32 v[56:57], v[2:3]
	v_mov_b64_e32 v[58:59], v[2:3]
	v_mov_b64_e32 v[60:61], v[2:3]
	v_mov_b64_e32 v[62:63], v[2:3]
	v_mov_b64_e32 v[64:65], v[2:3]
	v_mov_b64_e32 v[66:67], v[2:3]
	v_mov_b64_e32 v[68:69], v[2:3]
	v_mov_b64_e32 v[70:71], v[2:3]
	v_mov_b64_e32 v[72:73], v[2:3]
	v_mov_b64_e32 v[74:75], v[2:3]
	v_mov_b64_e32 v[76:77], v[2:3]
	v_mov_b64_e32 v[78:79], v[2:3]
	v_mov_b64_e32 v[80:81], v[2:3]
	v_mov_b64_e32 v[82:83], v[2:3]
	v_mov_b64_e32 v[84:85], v[2:3]
	v_mov_b64_e32 v[86:87], v[2:3]
	v_mov_b64_e32 v[88:89], v[2:3]
	v_mov_b64_e32 v[90:91], v[2:3]
	v_mov_b64_e32 v[92:93], v[2:3]
	v_mov_b64_e32 v[94:95], v[2:3]
	v_mov_b64_e32 v[96:97], v[2:3]
	v_mov_b64_e32 v[98:99], v[2:3]
	v_mov_b64_e32 v[100:101], v[2:3]
	v_mov_b64_e32 v[102:103], v[2:3]
	v_mov_b64_e32 v[104:105], v[2:3]
	v_mov_b64_e32 v[106:107], v[2:3]
	v_mov_b64_e32 v[108:109], v[2:3]
	v_mov_b64_e32 v[110:111], v[2:3]
	v_mov_b64_e32 v[112:113], v[2:3]
	v_mov_b64_e32 v[114:115], v[2:3]
	v_mov_b64_e32 v[116:117], v[2:3]
	v_mov_b64_e32 v[118:119], v[2:3]
	v_mov_b64_e32 v[120:121], v[2:3]
	v_mov_b64_e32 v[122:123], v[2:3]
	v_mov_b64_e32 v[124:125], v[2:3]
	v_mov_b64_e32 v[126:127], v[2:3]
	v_mov_b64_e32 v[128:129], v[2:3]

.LBB0_997:
	s_ashr_i32 s19, s18, 31
	s_lshl_b64 s[20:21], s[18:19], 19
	s_add_u32 s20, s58, s20
	s_addc_u32 s21, s59, s21
	s_and_b64 s[22:23], s[0:1], exec
	s_cselect_b32 s19, s21, s29
	s_cselect_b32 s46, s20, s28
	s_ashr_i32 s17, s16, 31
	s_lshl_b64 s[22:23], s[16:17], 19
	s_add_u32 s22, s86, s22
	s_addc_u32 s23, s87, s23
	s_and_b64 s[48:49], s[0:1], exec
	s_cselect_b32 s17, s23, s31
	s_cselect_b32 s47, s22, s30
	s_add_u32 s28, s28, 0x40080
	s_addc_u32 s29, s29, 0
	s_add_u32 s48, s30, 0x100
	v_mov_b64_e32 v[2:3], 0
	s_addc_u32 s49, s31, 0
	s_mov_b32 s50, -2
	v_mov_b64_e32 v[4:5], v[2:3]
	v_mov_b64_e32 v[6:7], v[2:3]
	v_mov_b64_e32 v[8:9], v[2:3]
	v_mov_b64_e32 v[10:11], v[2:3]
	v_mov_b64_e32 v[12:13], v[2:3]
	v_mov_b64_e32 v[14:15], v[2:3]
	v_mov_b64_e32 v[16:17], v[2:3]
	v_mov_b64_e32 v[18:19], v[2:3]
	v_mov_b64_e32 v[20:21], v[2:3]
	v_mov_b64_e32 v[22:23], v[2:3]
	v_mov_b64_e32 v[24:25], v[2:3]
	v_mov_b64_e32 v[26:27], v[2:3]
	v_mov_b64_e32 v[28:29], v[2:3]
	v_mov_b64_e32 v[30:31], v[2:3]
	v_mov_b64_e32 v[32:33], v[2:3]
	v_mov_b64_e32 v[34:35], v[2:3]
	v_mov_b64_e32 v[36:37], v[2:3]
	v_mov_b64_e32 v[38:39], v[2:3]
	v_mov_b64_e32 v[40:41], v[2:3]
	v_mov_b64_e32 v[42:43], v[2:3]
	v_mov_b64_e32 v[44:45], v[2:3]
	v_mov_b64_e32 v[46:47], v[2:3]
	v_mov_b64_e32 v[48:49], v[2:3]
	v_mov_b64_e32 v[50:51], v[2:3]
	v_mov_b64_e32 v[52:53], v[2:3]
	v_mov_b64_e32 v[54:55], v[2:3]
	v_mov_b64_e32 v[56:57], v[2:3]
	v_mov_b64_e32 v[58:59], v[2:3]
	v_mov_b64_e32 v[60:61], v[2:3]
	v_mov_b64_e32 v[62:63], v[2:3]
	v_mov_b64_e32 v[64:65], v[2:3]
	v_mov_b64_e32 v[66:67], v[2:3]
	v_mov_b64_e32 v[68:69], v[2:3]
	v_mov_b64_e32 v[70:71], v[2:3]
	v_mov_b64_e32 v[72:73], v[2:3]
	v_mov_b64_e32 v[74:75], v[2:3]
	v_mov_b64_e32 v[76:77], v[2:3]
	v_mov_b64_e32 v[78:79], v[2:3]
	v_mov_b64_e32 v[80:81], v[2:3]
	v_mov_b64_e32 v[82:83], v[2:3]
	v_mov_b64_e32 v[84:85], v[2:3]
	v_mov_b64_e32 v[86:87], v[2:3]
	v_mov_b64_e32 v[88:89], v[2:3]
	v_mov_b64_e32 v[90:91], v[2:3]
	v_mov_b64_e32 v[92:93], v[2:3]
	v_mov_b64_e32 v[94:95], v[2:3]
	v_mov_b64_e32 v[96:97], v[2:3]
	v_mov_b64_e32 v[98:99], v[2:3]
	v_mov_b64_e32 v[100:101], v[2:3]
	v_mov_b64_e32 v[102:103], v[2:3]
	v_mov_b64_e32 v[104:105], v[2:3]
	v_mov_b64_e32 v[106:107], v[2:3]
	v_mov_b64_e32 v[108:109], v[2:3]
	v_mov_b64_e32 v[110:111], v[2:3]
	v_mov_b64_e32 v[112:113], v[2:3]
	v_mov_b64_e32 v[114:115], v[2:3]
	v_mov_b64_e32 v[116:117], v[2:3]
	v_mov_b64_e32 v[118:119], v[2:3]
	v_mov_b64_e32 v[120:121], v[2:3]
	v_mov_b64_e32 v[122:123], v[2:3]
	v_mov_b64_e32 v[124:125], v[2:3]
	v_mov_b64_e32 v[126:127], v[2:3]
	v_mov_b64_e32 v[128:129], v[2:3]

.LBB0_1592:
	s_ashr_i32 s19, s18, 31
	s_lshl_b64 s[20:21], s[18:19], 19
	s_add_u32 s20, s58, s20
	s_addc_u32 s21, s59, s21
	s_and_b64 s[22:23], s[0:1], exec
	s_cselect_b32 s19, s21, s27
	s_cselect_b32 s48, s20, s26
	s_ashr_i32 s17, s16, 31
	s_lshl_b64 s[22:23], s[16:17], 19
	v_readlane_b32 s30, v251, 4
	v_readlane_b32 s31, v251, 5
	s_add_u32 s22, s30, s22
	s_addc_u32 s23, s31, s23
	s_and_b64 s[30:31], s[0:1], exec
	s_cselect_b32 s17, s23, s29
	s_cselect_b32 s49, s22, s28
	s_add_u32 s26, s26, 0x40080
	s_addc_u32 s27, s27, 0
	s_add_u32 s50, s28, 0x100
	v_mov_b64_e32 v[2:3], 0
	s_addc_u32 s51, s29, 0
	s_mov_b32 s54, -2
	v_mov_b64_e32 v[4:5], v[2:3]
	v_mov_b64_e32 v[6:7], v[2:3]
	v_mov_b64_e32 v[8:9], v[2:3]
	v_mov_b64_e32 v[10:11], v[2:3]
	v_mov_b64_e32 v[12:13], v[2:3]
	v_mov_b64_e32 v[14:15], v[2:3]
	v_mov_b64_e32 v[16:17], v[2:3]
	v_mov_b64_e32 v[18:19], v[2:3]
	v_mov_b64_e32 v[20:21], v[2:3]
	v_mov_b64_e32 v[22:23], v[2:3]
	v_mov_b64_e32 v[24:25], v[2:3]
	v_mov_b64_e32 v[26:27], v[2:3]
	v_mov_b64_e32 v[28:29], v[2:3]
	v_mov_b64_e32 v[30:31], v[2:3]
	v_mov_b64_e32 v[32:33], v[2:3]
	v_mov_b64_e32 v[34:35], v[2:3]
	v_mov_b64_e32 v[36:37], v[2:3]
	v_mov_b64_e32 v[38:39], v[2:3]
	v_mov_b64_e32 v[40:41], v[2:3]
	v_mov_b64_e32 v[42:43], v[2:3]
	v_mov_b64_e32 v[44:45], v[2:3]
	v_mov_b64_e32 v[46:47], v[2:3]
	v_mov_b64_e32 v[48:49], v[2:3]
	v_mov_b64_e32 v[50:51], v[2:3]
	v_mov_b64_e32 v[52:53], v[2:3]
	v_mov_b64_e32 v[54:55], v[2:3]
	v_mov_b64_e32 v[56:57], v[2:3]
	v_mov_b64_e32 v[58:59], v[2:3]
	v_mov_b64_e32 v[60:61], v[2:3]
	v_mov_b64_e32 v[62:63], v[2:3]
	v_mov_b64_e32 v[64:65], v[2:3]
	v_mov_b64_e32 v[66:67], v[2:3]
	v_mov_b64_e32 v[68:69], v[2:3]
	v_mov_b64_e32 v[70:71], v[2:3]
	v_mov_b64_e32 v[72:73], v[2:3]
	v_mov_b64_e32 v[74:75], v[2:3]
	v_mov_b64_e32 v[76:77], v[2:3]
	v_mov_b64_e32 v[78:79], v[2:3]
	v_mov_b64_e32 v[80:81], v[2:3]
	v_mov_b64_e32 v[82:83], v[2:3]
	v_mov_b64_e32 v[84:85], v[2:3]
	v_mov_b64_e32 v[86:87], v[2:3]
	v_mov_b64_e32 v[88:89], v[2:3]
	v_mov_b64_e32 v[90:91], v[2:3]
	v_mov_b64_e32 v[92:93], v[2:3]
	v_mov_b64_e32 v[94:95], v[2:3]
	v_mov_b64_e32 v[96:97], v[2:3]
	v_mov_b64_e32 v[98:99], v[2:3]
	v_mov_b64_e32 v[100:101], v[2:3]
	v_mov_b64_e32 v[102:103], v[2:3]
	v_mov_b64_e32 v[104:105], v[2:3]
	v_mov_b64_e32 v[106:107], v[2:3]
	v_mov_b64_e32 v[108:109], v[2:3]
	v_mov_b64_e32 v[110:111], v[2:3]
	v_mov_b64_e32 v[112:113], v[2:3]
	v_mov_b64_e32 v[114:115], v[2:3]
	v_mov_b64_e32 v[116:117], v[2:3]
	v_mov_b64_e32 v[118:119], v[2:3]
	v_mov_b64_e32 v[120:121], v[2:3]
	v_mov_b64_e32 v[122:123], v[2:3]
	v_mov_b64_e32 v[124:125], v[2:3]
	v_mov_b64_e32 v[126:127], v[2:3]
	v_mov_b64_e32 v[128:129], v[2:3]
